# convnt: P3 short-conv row loads and full-line b_gate stores carry nt (streaming) so they do not displace the K-tiles of the 96 GEMM workgroups running concurrently
# speedup vs baseline: 1.0059x; 1.0059x over previous
.LBB0_834:
	s_or_b64 exec, exec, s[0:1]
	s_waitcnt vmcnt(1)
	v_pk_mul_f32 v[50:51], v[20:21], v[4:5]
	s_waitcnt vmcnt(0)
	v_pk_mul_f32 v[52:53], v[26:27], v[6:7]
	v_pk_mul_f32 v[54:55], v[28:29], v[8:9]
	v_pk_mul_f32 v[56:57], v[18:19], v[2:3]
	v_lshlrev_b32_e32 v150, 16, v38
	v_and_b32_e32 v151, 0xffff0000, v38
	v_lshlrev_b32_e32 v152, 16, v39
	v_and_b32_e32 v153, 0xffff0000, v39
	v_lshlrev_b32_e32 v154, 16, v40
	v_and_b32_e32 v155, 0xffff0000, v40
	v_lshlrev_b32_e32 v156, 16, v41
	v_and_b32_e32 v157, 0xffff0000, v41
	v_pk_fma_f32 v[48:49], v[12:13], v[48:49], v[54:55]
	v_pk_fma_f32 v[46:47], v[10:11], v[46:47], v[52:53]
	v_pk_fma_f32 v[44:45], v[16:17], v[44:45], v[50:51]
	v_pk_fma_f32 v[42:43], v[14:15], v[42:43], v[56:57]
	v_lshlrev_b32_e32 v38, 16, v34
	v_and_b32_e32 v39, 0xffff0000, v34
	v_lshlrev_b32_e32 v34, 16, v35
	v_and_b32_e32 v35, 0xffff0000, v35
	v_lshlrev_b32_e32 v40, 16, v36
	v_and_b32_e32 v41, 0xffff0000, v36
	v_lshlrev_b32_e32 v36, 16, v37
	v_and_b32_e32 v37, 0xffff0000, v37
	v_pk_fma_f32 v[42:43], v[22:23], v[150:151], v[42:43]
	v_pk_fma_f32 v[44:45], v[24:25], v[152:153], v[44:45]
	v_pk_fma_f32 v[46:47], v[30:31], v[154:155], v[46:47]
	v_pk_fma_f32 v[48:49], v[32:33], v[156:157], v[48:49]
	s_nop 0
	v_pk_mul_f32 v[48:49], v[48:49], v[36:37]
	v_pk_mul_f32 v[36:37], v[46:47], v[40:41]
	v_pk_mul_f32 v[40:41], v[44:45], v[34:35]
	v_pk_mul_f32 v[34:35], v[42:43], v[38:39]
	s_nop 0
	v_cvt_pk_bf16_f32 v34, v34, v35
	v_cvt_pk_bf16_f32 v35, v40, v41
	v_cvt_pk_bf16_f32 v36, v36, v37
	v_cvt_pk_bf16_f32 v37, v48, v49
	global_store_dwordx4 v[130:131], v[34:37], off nt
	s_nop 1
	v_add_u32_e32 v35, 18, v114
	v_add_u32_e32 v34, 9, v114
	v_cmp_gt_i32_e32 vcc, v35, v116
	s_or_b64 s[10:11], vcc, s[10:11]
	v_mov_b32_e32 v114, v34
	s_andn2_b64 exec, exec, s[10:11]
	s_cbranch_execz .LBB0_853
.LBB0_835:
	v_mov_b32_e32 v132, v114
	s_nop 0
	v_ashrrev_i32_e32 v133, 31, v132
	v_add_u32_e32 v170, 1, v132
	v_lshlrev_b64 v[34:35], 11, v[132:133]
	v_ashrrev_i32_e32 v171, 31, v170
	v_add_u32_e32 v168, 2, v132
	v_lshl_add_u64 v[36:37], v[124:125], 0, v[34:35]
	v_lshl_add_u64 v[172:173], v[126:127], 0, v[34:35]
	v_lshlrev_b64 v[34:35], 11, v[170:171]
	v_ashrrev_i32_e32 v169, 31, v168
	v_add_u32_e32 v162, 3, v132
	v_lshl_add_u64 v[38:39], v[124:125], 0, v[34:35]
	v_lshl_add_u64 v[166:167], v[126:127], 0, v[34:35]
	v_lshlrev_b64 v[34:35], 11, v[168:169]
	v_ashrrev_i32_e32 v163, 31, v162
	v_add_u32_e32 v160, 4, v132
	v_lshl_add_u64 v[40:41], v[124:125], 0, v[34:35]
	v_lshl_add_u64 v[164:165], v[126:127], 0, v[34:35]
	v_lshlrev_b64 v[34:35], 11, v[162:163]
	v_ashrrev_i32_e32 v161, 31, v160
	v_add_u32_e32 v146, 5, v132
	global_load_dwordx4 v[98:101], v[172:173], off nt
	global_load_dwordx4 v[90:93], v[166:167], off nt
	global_load_dwordx4 v[94:97], v[38:39], off nt
	global_load_dwordx4 v[82:85], v[40:41], off nt
	v_lshl_add_u64 v[38:39], v[124:125], 0, v[34:35]
	v_lshl_add_u64 v[158:159], v[126:127], 0, v[34:35]
	v_lshlrev_b64 v[34:35], 11, v[160:161]
	v_ashrrev_i32_e32 v147, 31, v146
	v_add_u32_e32 v144, 6, v132
	v_lshl_add_u64 v[40:41], v[124:125], 0, v[34:35]
	v_lshl_add_u64 v[148:149], v[126:127], 0, v[34:35]
	v_lshlrev_b64 v[34:35], 11, v[146:147]
	v_ashrrev_i32_e32 v145, 31, v144
	v_add_u32_e32 v138, 7, v132
	global_load_dwordx4 v[86:89], v[164:165], off nt
	global_load_dwordx4 v[74:77], v[158:159], off nt
	global_load_dwordx4 v[78:81], v[38:39], off nt
	global_load_dwordx4 v[66:69], v[40:41], off nt
	v_lshl_add_u64 v[38:39], v[124:125], 0, v[34:35]
	v_lshl_add_u64 v[142:143], v[126:127], 0, v[34:35]
	v_lshlrev_b64 v[34:35], 11, v[144:145]
	v_ashrrev_i32_e32 v139, 31, v138
	v_add_u32_e32 v136, 8, v132
	v_lshl_add_u64 v[40:41], v[124:125], 0, v[34:35]
	v_lshl_add_u64 v[140:141], v[126:127], 0, v[34:35]
	v_lshlrev_b64 v[34:35], 11, v[138:139]
	v_ashrrev_i32_e32 v137, 31, v136
	global_load_dwordx4 v[70:73], v[148:149], off nt
	global_load_dwordx4 v[58:61], v[142:143], off nt
	global_load_dwordx4 v[62:65], v[38:39], off nt
	global_load_dwordx4 v[50:53], v[40:41], off nt
	v_lshl_add_u64 v[38:39], v[124:125], 0, v[34:35]
	v_lshl_add_u64 v[134:135], v[126:127], 0, v[34:35]
	v_lshlrev_b64 v[34:35], 11, v[136:137]
	v_lshl_add_u64 v[40:41], v[124:125], 0, v[34:35]
	global_load_dwordx4 v[54:57], v[140:141], off nt
	global_load_dwordx4 v[42:45], v[134:135], off nt
	global_load_dwordx4 v[46:49], v[38:39], off nt
	s_nop 0
	global_load_dwordx4 v[38:41], v[40:41], off nt
	v_lshl_add_u64 v[130:131], v[126:127], 0, v[34:35]
	global_load_dwordx4 v[110:113], v[36:37], off nt
	s_nop 0
	global_load_dwordx4 v[34:37], v[130:131], off nt
	v_cmp_gt_i32_e32 vcc, s3, v132
	s_nop 1
	v_cndmask_b32_e32 v102, 31, v115, vcc
	v_and_b32_e32 v102, v102, v132
	v_cmp_ne_u32_e64 s[0:1], 0, v102
	s_nor_b64 s[12:13], vcc, s[0:1]
	s_nop 0
	v_cndmask_b32_e64 v102, 0, v2, s[0:1]
	v_cndmask_b32_e64 v103, 0, v3, s[0:1]
	v_cndmask_b32_e64 v104, 0, v4, s[0:1]
	v_cndmask_b32_e64 v105, 0, v5, s[0:1]
	v_cndmask_b32_e64 v106, 0, v6, s[0:1]
	v_cndmask_b32_e64 v107, 0, v7, s[0:1]
	v_cndmask_b32_e64 v108, 0, v8, s[0:1]
	v_cndmask_b32_e64 v109, 0, v9, s[0:1]
	v_cndmask_b32_e64 v5, 0, v157, s[0:1]
	v_cndmask_b32_e64 v4, 0, v156, s[0:1]
	v_cndmask_b32_e64 v3, 0, v155, s[0:1]
	v_cndmask_b32_e64 v2, 0, v154, s[0:1]
	v_cndmask_b32_e64 v9, 0, v153, s[0:1]
	v_cndmask_b32_e64 v8, 0, v152, s[0:1]
	v_cndmask_b32_e64 v7, 0, v151, s[0:1]
	v_cndmask_b32_e64 v6, 0, v150, s[0:1]
	s_and_saveexec_b64 s[0:1], s[12:13]
	s_cbranch_execz .LBB0_837
	v_add_u32_e32 v2, 0xffffc000, v132
	v_lshrrev_b32_e32 v2, 4, v2
	v_and_b32_e32 v122, 0xffffffe, v2
	v_lshlrev_b64 v[2:3], 12, v[122:123]
	v_lshl_add_u64 v[2:3], v[128:129], 0, v[2:3]
	global_load_dwordx4 v[102:105], v[2:3], off
	global_load_dwordx4 v[106:109], v[2:3], off offset:16
	v_lshl_add_u64 v[4:5], v[2:3], 0, s[24:25]
	v_add_co_u32_e32 v2, vcc, 0x1000, v2
	s_nop 1
	v_addc_co_u32_e32 v3, vcc, 0, v3, vcc
	global_load_dwordx4 v[6:9], v[2:3], off
	s_nop 0
	global_load_dwordx4 v[2:5], v[4:5], off offset:16
.LBB0_837:
	s_or_b64 exec, exec, s[0:1]
	s_waitcnt vmcnt(1)
	v_pk_mul_f32 v[174:175], v[20:21], v[8:9]
	v_pk_mul_f32 v[180:181], v[18:19], v[6:7]
	v_lshlrev_b32_e32 v150, 16, v110
	v_and_b32_e32 v151, 0xffff0000, v110
	v_lshlrev_b32_e32 v110, 16, v111
	v_and_b32_e32 v111, 0xffff0000, v111
	s_waitcnt vmcnt(0)
	v_pk_mul_f32 v[176:177], v[26:27], v[2:3]
	v_pk_mul_f32 v[178:179], v[28:29], v[4:5]
	v_pk_fma_f32 v[104:105], v[16:17], v[104:105], v[174:175]
	v_pk_fma_f32 v[102:103], v[14:15], v[102:103], v[180:181]
	v_lshlrev_b32_e32 v152, 16, v112
	v_and_b32_e32 v153, 0xffff0000, v112
	v_lshlrev_b32_e32 v112, 16, v113
	v_and_b32_e32 v113, 0xffff0000, v113
	v_lshlrev_b32_e32 v154, 16, v98
	v_and_b32_e32 v155, 0xffff0000, v98
	v_lshlrev_b32_e32 v98, 16, v99
	v_and_b32_e32 v99, 0xffff0000, v99
	v_pk_fma_f32 v[108:109], v[12:13], v[108:109], v[178:179]
	v_pk_fma_f32 v[106:107], v[10:11], v[106:107], v[176:177]
	v_pk_fma_f32 v[102:103], v[22:23], v[150:151], v[102:103]
	v_pk_fma_f32 v[104:105], v[24:25], v[110:111], v[104:105]
	v_lshlrev_b32_e32 v156, 16, v100
	v_and_b32_e32 v157, 0xffff0000, v100
	v_lshlrev_b32_e32 v100, 16, v101
	v_and_b32_e32 v101, 0xffff0000, v101
	v_pk_fma_f32 v[106:107], v[30:31], v[152:153], v[106:107]
	v_pk_fma_f32 v[108:109], v[32:33], v[112:113], v[108:109]
	v_pk_mul_f32 v[104:105], v[104:105], v[98:99]
	v_pk_mul_f32 v[98:99], v[102:103], v[154:155]
	v_pk_mul_f32 v[108:109], v[108:109], v[100:101]
	v_pk_mul_f32 v[100:101], v[106:107], v[156:157]
	v_cvt_pk_bf16_f32 v98, v98, v99
	v_cmp_gt_i32_e32 vcc, s26, v132
	v_cvt_pk_bf16_f32 v99, v104, v105
	v_cvt_pk_bf16_f32 v100, v100, v101
	v_cvt_pk_bf16_f32 v101, v108, v109
	global_store_dwordx4 v[172:173], v[98:101], off nt
	s_nop 1
	v_cndmask_b32_e32 v98, 31, v115, vcc
	v_and_b32_e32 v98, v98, v170
	v_cmp_ne_u32_e64 s[0:1], 0, v98
	s_nor_b64 s[12:13], vcc, s[0:1]
	s_nop 0
	v_cndmask_b32_e64 v98, 0, v6, s[0:1]
	v_cndmask_b32_e64 v99, 0, v7, s[0:1]
	v_cndmask_b32_e64 v100, 0, v8, s[0:1]
	v_cndmask_b32_e64 v101, 0, v9, s[0:1]
	v_cndmask_b32_e64 v102, 0, v2, s[0:1]
	v_cndmask_b32_e64 v103, 0, v3, s[0:1]
	v_cndmask_b32_e64 v104, 0, v4, s[0:1]
	v_cndmask_b32_e64 v105, 0, v5, s[0:1]
	v_cndmask_b32_e64 v5, 0, v113, s[0:1]
	v_cndmask_b32_e64 v4, 0, v112, s[0:1]
	v_cndmask_b32_e64 v3, 0, v153, s[0:1]
	v_cndmask_b32_e64 v2, 0, v152, s[0:1]
	v_cndmask_b32_e64 v9, 0, v111, s[0:1]
	v_cndmask_b32_e64 v8, 0, v110, s[0:1]
	v_cndmask_b32_e64 v7, 0, v151, s[0:1]
	v_cndmask_b32_e64 v6, 0, v150, s[0:1]
	s_and_saveexec_b64 s[0:1], s[12:13]
	s_cbranch_execz .LBB0_839
	v_add_u32_e32 v2, 0xffffc001, v132
	v_lshrrev_b32_e32 v2, 4, v2
	v_and_b32_e32 v122, 0xffffffe, v2
	v_lshlrev_b64 v[2:3], 12, v[122:123]
	v_lshl_add_u64 v[2:3], v[128:129], 0, v[2:3]
	global_load_dwordx4 v[98:101], v[2:3], off
	global_load_dwordx4 v[102:105], v[2:3], off offset:16
	v_lshl_add_u64 v[4:5], v[2:3], 0, s[24:25]
	v_add_co_u32_e32 v2, vcc, 0x1000, v2
	s_nop 1
	v_addc_co_u32_e32 v3, vcc, 0, v3, vcc
	global_load_dwordx4 v[6:9], v[2:3], off
	s_nop 0
	global_load_dwordx4 v[2:5], v[4:5], off offset:16
.LBB0_839:
	s_or_b64 exec, exec, s[0:1]
	s_waitcnt vmcnt(1)
	v_pk_mul_f32 v[150:151], v[20:21], v[8:9]
	s_waitcnt vmcnt(0)
	v_pk_mul_f32 v[152:153], v[26:27], v[2:3]
	v_pk_mul_f32 v[154:155], v[28:29], v[4:5]
	v_pk_mul_f32 v[156:157], v[18:19], v[6:7]
	v_lshlrev_b32_e32 v106, 16, v94
	v_and_b32_e32 v107, 0xffff0000, v94
	v_lshlrev_b32_e32 v108, 16, v95
	v_and_b32_e32 v109, 0xffff0000, v95
	v_lshlrev_b32_e32 v110, 16, v96
	v_and_b32_e32 v111, 0xffff0000, v96
	v_lshlrev_b32_e32 v112, 16, v97
	v_and_b32_e32 v113, 0xffff0000, v97
	v_pk_fma_f32 v[104:105], v[12:13], v[104:105], v[154:155]
	v_pk_fma_f32 v[102:103], v[10:11], v[102:103], v[152:153]
	v_pk_fma_f32 v[100:101], v[16:17], v[100:101], v[150:151]
	v_pk_fma_f32 v[98:99], v[14:15], v[98:99], v[156:157]
	v_lshlrev_b32_e32 v94, 16, v90
	v_and_b32_e32 v95, 0xffff0000, v90
	v_lshlrev_b32_e32 v90, 16, v91
	v_and_b32_e32 v91, 0xffff0000, v91
	v_lshlrev_b32_e32 v96, 16, v92
	v_and_b32_e32 v97, 0xffff0000, v92
	v_lshlrev_b32_e32 v92, 16, v93
	v_and_b32_e32 v93, 0xffff0000, v93
	v_pk_fma_f32 v[98:99], v[22:23], v[106:107], v[98:99]
	v_pk_fma_f32 v[100:101], v[24:25], v[108:109], v[100:101]
	v_pk_fma_f32 v[102:103], v[30:31], v[110:111], v[102:103]
	v_pk_fma_f32 v[104:105], v[32:33], v[112:113], v[104:105]
	v_cmp_gt_i32_e32 vcc, s27, v132
	v_pk_mul_f32 v[104:105], v[104:105], v[92:93]
	v_pk_mul_f32 v[92:93], v[102:103], v[96:97]
	v_pk_mul_f32 v[96:97], v[100:101], v[90:91]
	v_pk_mul_f32 v[90:91], v[98:99], v[94:95]
	s_nop 0
	v_cvt_pk_bf16_f32 v90, v90, v91
	v_cvt_pk_bf16_f32 v91, v96, v97
	v_cvt_pk_bf16_f32 v92, v92, v93
	v_cvt_pk_bf16_f32 v93, v104, v105
	global_store_dwordx4 v[166:167], v[90:93], off nt
	s_nop 1
	v_cndmask_b32_e32 v90, 31, v115, vcc
	v_and_b32_e32 v90, v90, v168
	v_cmp_ne_u32_e64 s[0:1], 0, v90
	s_nor_b64 s[12:13], vcc, s[0:1]
	s_nop 0
	v_cndmask_b32_e64 v90, 0, v6, s[0:1]
	v_cndmask_b32_e64 v91, 0, v7, s[0:1]
	v_cndmask_b32_e64 v92, 0, v8, s[0:1]
	v_cndmask_b32_e64 v93, 0, v9, s[0:1]
	v_cndmask_b32_e64 v94, 0, v2, s[0:1]
	v_cndmask_b32_e64 v95, 0, v3, s[0:1]
	v_cndmask_b32_e64 v96, 0, v4, s[0:1]
	v_cndmask_b32_e64 v97, 0, v5, s[0:1]
	v_cndmask_b32_e64 v5, 0, v113, s[0:1]
	v_cndmask_b32_e64 v4, 0, v112, s[0:1]
	v_cndmask_b32_e64 v3, 0, v111, s[0:1]
	v_cndmask_b32_e64 v2, 0, v110, s[0:1]
	v_cndmask_b32_e64 v9, 0, v109, s[0:1]
	v_cndmask_b32_e64 v8, 0, v108, s[0:1]
	v_cndmask_b32_e64 v7, 0, v107, s[0:1]
	v_cndmask_b32_e64 v6, 0, v106, s[0:1]
	s_and_saveexec_b64 s[0:1], s[12:13]
	s_cbranch_execz .LBB0_841
	v_add_u32_e32 v2, 0xffffc002, v132
	v_lshrrev_b32_e32 v2, 4, v2
	v_and_b32_e32 v122, 0xffffffe, v2
	v_lshlrev_b64 v[2:3], 12, v[122:123]
	v_lshl_add_u64 v[2:3], v[128:129], 0, v[2:3]
	global_load_dwordx4 v[90:93], v[2:3], off
	global_load_dwordx4 v[94:97], v[2:3], off offset:16
	v_lshl_add_u64 v[4:5], v[2:3], 0, s[24:25]
	v_add_co_u32_e32 v2, vcc, 0x1000, v2
	s_nop 1
	v_addc_co_u32_e32 v3, vcc, 0, v3, vcc
	global_load_dwordx4 v[6:9], v[2:3], off
	s_nop 0
	global_load_dwordx4 v[2:5], v[4:5], off offset:16
.LBB0_841:
	s_or_b64 exec, exec, s[0:1]
	s_waitcnt vmcnt(1)
	v_pk_mul_f32 v[112:113], v[18:19], v[6:7]
	v_lshlrev_b32_e32 v98, 16, v82
	v_and_b32_e32 v99, 0xffff0000, v82
	v_pk_mul_f32 v[106:107], v[20:21], v[8:9]
	v_pk_fma_f32 v[90:91], v[14:15], v[90:91], v[112:113]
	v_lshlrev_b32_e32 v100, 16, v83
	v_and_b32_e32 v101, 0xffff0000, v83
	v_lshlrev_b32_e32 v82, 16, v86
	v_and_b32_e32 v83, 0xffff0000, v86
	s_waitcnt vmcnt(0)
	v_pk_mul_f32 v[108:109], v[26:27], v[2:3]
	v_pk_mul_f32 v[110:111], v[28:29], v[4:5]
	v_pk_fma_f32 v[92:93], v[16:17], v[92:93], v[106:107]
	v_pk_fma_f32 v[90:91], v[22:23], v[98:99], v[90:91]
	v_lshlrev_b32_e32 v102, 16, v84
	v_and_b32_e32 v103, 0xffff0000, v84
	v_lshlrev_b32_e32 v104, 16, v85
	v_and_b32_e32 v105, 0xffff0000, v85
	v_lshlrev_b32_e32 v84, 16, v87
	v_and_b32_e32 v85, 0xffff0000, v87
	v_pk_fma_f32 v[96:97], v[12:13], v[96:97], v[110:111]
	v_pk_fma_f32 v[94:95], v[10:11], v[94:95], v[108:109]
	v_pk_fma_f32 v[92:93], v[24:25], v[100:101], v[92:93]
	v_pk_mul_f32 v[82:83], v[90:91], v[82:83]
	v_lshlrev_b32_e32 v86, 16, v88
	v_and_b32_e32 v87, 0xffff0000, v88
	v_lshlrev_b32_e32 v88, 16, v89
	v_and_b32_e32 v89, 0xffff0000, v89
	v_pk_fma_f32 v[94:95], v[30:31], v[102:103], v[94:95]
	v_pk_fma_f32 v[96:97], v[32:33], v[104:105], v[96:97]
	v_pk_mul_f32 v[84:85], v[92:93], v[84:85]
	v_cvt_pk_bf16_f32 v82, v82, v83
	v_cmp_gt_i32_e32 vcc, s28, v132
	v_pk_mul_f32 v[88:89], v[96:97], v[88:89]
	v_pk_mul_f32 v[86:87], v[94:95], v[86:87]
	v_cvt_pk_bf16_f32 v83, v84, v85
	s_nop 0
	v_cvt_pk_bf16_f32 v84, v86, v87
	v_cvt_pk_bf16_f32 v85, v88, v89
	global_store_dwordx4 v[164:165], v[82:85], off nt
	s_nop 1
	v_cndmask_b32_e32 v82, 31, v115, vcc
	v_and_b32_e32 v82, v82, v162
	v_cmp_ne_u32_e64 s[0:1], 0, v82
	s_nor_b64 s[12:13], vcc, s[0:1]
	s_nop 0
	v_cndmask_b32_e64 v82, 0, v6, s[0:1]
	v_cndmask_b32_e64 v83, 0, v7, s[0:1]
	v_cndmask_b32_e64 v84, 0, v8, s[0:1]
	v_cndmask_b32_e64 v85, 0, v9, s[0:1]
	v_cndmask_b32_e64 v86, 0, v2, s[0:1]
	v_cndmask_b32_e64 v87, 0, v3, s[0:1]
	v_cndmask_b32_e64 v88, 0, v4, s[0:1]
	v_cndmask_b32_e64 v89, 0, v5, s[0:1]
	v_cndmask_b32_e64 v5, 0, v105, s[0:1]
	v_cndmask_b32_e64 v4, 0, v104, s[0:1]
	v_cndmask_b32_e64 v3, 0, v103, s[0:1]
	v_cndmask_b32_e64 v2, 0, v102, s[0:1]
	v_cndmask_b32_e64 v9, 0, v101, s[0:1]
	v_cndmask_b32_e64 v8, 0, v100, s[0:1]
	v_cndmask_b32_e64 v7, 0, v99, s[0:1]
	v_cndmask_b32_e64 v6, 0, v98, s[0:1]
	s_and_saveexec_b64 s[0:1], s[12:13]
	s_cbranch_execz .LBB0_843
	v_add_u32_e32 v2, 0xffffc003, v132
	v_lshrrev_b32_e32 v2, 4, v2
	v_and_b32_e32 v122, 0xffffffe, v2
	v_lshlrev_b64 v[2:3], 12, v[122:123]
	v_lshl_add_u64 v[2:3], v[128:129], 0, v[2:3]
	global_load_dwordx4 v[82:85], v[2:3], off
	global_load_dwordx4 v[86:89], v[2:3], off offset:16
	v_lshl_add_u64 v[4:5], v[2:3], 0, s[24:25]
	v_add_co_u32_e32 v2, vcc, 0x1000, v2
	s_nop 1
	v_addc_co_u32_e32 v3, vcc, 0, v3, vcc
	global_load_dwordx4 v[6:9], v[2:3], off
	s_nop 0
	global_load_dwordx4 v[2:5], v[4:5], off offset:16
.LBB0_843:
	s_or_b64 exec, exec, s[0:1]
	s_waitcnt vmcnt(1)
	v_pk_mul_f32 v[98:99], v[20:21], v[8:9]
	s_waitcnt vmcnt(0)
	v_pk_mul_f32 v[100:101], v[26:27], v[2:3]
	v_pk_mul_f32 v[102:103], v[28:29], v[4:5]
	v_pk_mul_f32 v[104:105], v[18:19], v[6:7]
	v_lshlrev_b32_e32 v90, 16, v78
	v_and_b32_e32 v91, 0xffff0000, v78
	v_lshlrev_b32_e32 v92, 16, v79
	v_and_b32_e32 v93, 0xffff0000, v79
	v_lshlrev_b32_e32 v94, 16, v80
	v_and_b32_e32 v95, 0xffff0000, v80
	v_lshlrev_b32_e32 v96, 16, v81
	v_and_b32_e32 v97, 0xffff0000, v81
	v_pk_fma_f32 v[88:89], v[12:13], v[88:89], v[102:103]
	v_pk_fma_f32 v[86:87], v[10:11], v[86:87], v[100:101]
	v_pk_fma_f32 v[84:85], v[16:17], v[84:85], v[98:99]
	v_pk_fma_f32 v[82:83], v[14:15], v[82:83], v[104:105]
	v_lshlrev_b32_e32 v78, 16, v74
	v_and_b32_e32 v79, 0xffff0000, v74
	v_lshlrev_b32_e32 v74, 16, v75
	v_and_b32_e32 v75, 0xffff0000, v75
	v_lshlrev_b32_e32 v80, 16, v76
	v_and_b32_e32 v81, 0xffff0000, v76
	v_lshlrev_b32_e32 v76, 16, v77
	v_and_b32_e32 v77, 0xffff0000, v77
	v_pk_fma_f32 v[82:83], v[22:23], v[90:91], v[82:83]
	v_pk_fma_f32 v[84:85], v[24:25], v[92:93], v[84:85]
	v_pk_fma_f32 v[86:87], v[30:31], v[94:95], v[86:87]
	v_pk_fma_f32 v[88:89], v[32:33], v[96:97], v[88:89]
	v_cmp_gt_i32_e32 vcc, s29, v132
	v_pk_mul_f32 v[88:89], v[88:89], v[76:77]
	v_pk_mul_f32 v[76:77], v[86:87], v[80:81]
	v_pk_mul_f32 v[80:81], v[84:85], v[74:75]
	v_pk_mul_f32 v[74:75], v[82:83], v[78:79]
	s_nop 0
	v_cvt_pk_bf16_f32 v74, v74, v75
	v_cvt_pk_bf16_f32 v75, v80, v81
	v_cvt_pk_bf16_f32 v76, v76, v77
	v_cvt_pk_bf16_f32 v77, v88, v89
	global_store_dwordx4 v[158:159], v[74:77], off nt
	s_nop 1
	v_cndmask_b32_e32 v74, 31, v115, vcc
	v_and_b32_e32 v74, v74, v160
	v_cmp_ne_u32_e64 s[0:1], 0, v74
	s_nor_b64 s[12:13], vcc, s[0:1]
	s_nop 0
	v_cndmask_b32_e64 v74, 0, v6, s[0:1]
	v_cndmask_b32_e64 v75, 0, v7, s[0:1]
	v_cndmask_b32_e64 v76, 0, v8, s[0:1]
	v_cndmask_b32_e64 v77, 0, v9, s[0:1]
	v_cndmask_b32_e64 v78, 0, v2, s[0:1]
	v_cndmask_b32_e64 v79, 0, v3, s[0:1]
	v_cndmask_b32_e64 v80, 0, v4, s[0:1]
	v_cndmask_b32_e64 v81, 0, v5, s[0:1]
	v_cndmask_b32_e64 v5, 0, v97, s[0:1]
	v_cndmask_b32_e64 v4, 0, v96, s[0:1]
	v_cndmask_b32_e64 v3, 0, v95, s[0:1]
	v_cndmask_b32_e64 v2, 0, v94, s[0:1]
	v_cndmask_b32_e64 v9, 0, v93, s[0:1]
	v_cndmask_b32_e64 v8, 0, v92, s[0:1]
	v_cndmask_b32_e64 v7, 0, v91, s[0:1]
	v_cndmask_b32_e64 v6, 0, v90, s[0:1]
	s_and_saveexec_b64 s[0:1], s[12:13]
	s_cbranch_execz .LBB0_845
	v_add_u32_e32 v2, 0xffffc004, v132
	v_lshrrev_b32_e32 v2, 4, v2
	v_and_b32_e32 v122, 0xffffffe, v2
	v_lshlrev_b64 v[2:3], 12, v[122:123]
	v_lshl_add_u64 v[2:3], v[128:129], 0, v[2:3]
	global_load_dwordx4 v[74:77], v[2:3], off
	global_load_dwordx4 v[78:81], v[2:3], off offset:16
	v_lshl_add_u64 v[4:5], v[2:3], 0, s[24:25]
	v_add_co_u32_e32 v2, vcc, 0x1000, v2
	s_nop 1
	v_addc_co_u32_e32 v3, vcc, 0, v3, vcc
	global_load_dwordx4 v[6:9], v[2:3], off
	s_nop 0
	global_load_dwordx4 v[2:5], v[4:5], off offset:16
.LBB0_845:
	s_or_b64 exec, exec, s[0:1]
	s_waitcnt vmcnt(1)
	v_pk_mul_f32 v[96:97], v[18:19], v[6:7]
	v_lshlrev_b32_e32 v82, 16, v66
	v_and_b32_e32 v83, 0xffff0000, v66
	v_pk_mul_f32 v[90:91], v[20:21], v[8:9]
	v_pk_fma_f32 v[74:75], v[14:15], v[74:75], v[96:97]
	v_lshlrev_b32_e32 v84, 16, v67
	v_and_b32_e32 v85, 0xffff0000, v67
	v_lshlrev_b32_e32 v66, 16, v70
	v_and_b32_e32 v67, 0xffff0000, v70
	s_waitcnt vmcnt(0)
	v_pk_mul_f32 v[92:93], v[26:27], v[2:3]
	v_pk_mul_f32 v[94:95], v[28:29], v[4:5]
	v_pk_fma_f32 v[76:77], v[16:17], v[76:77], v[90:91]
	v_pk_fma_f32 v[74:75], v[22:23], v[82:83], v[74:75]
	v_lshlrev_b32_e32 v86, 16, v68
	v_and_b32_e32 v87, 0xffff0000, v68
	v_lshlrev_b32_e32 v88, 16, v69
	v_and_b32_e32 v89, 0xffff0000, v69
	v_lshlrev_b32_e32 v68, 16, v71
	v_and_b32_e32 v69, 0xffff0000, v71
	v_pk_fma_f32 v[80:81], v[12:13], v[80:81], v[94:95]
	v_pk_fma_f32 v[78:79], v[10:11], v[78:79], v[92:93]
	v_pk_fma_f32 v[76:77], v[24:25], v[84:85], v[76:77]
	v_pk_mul_f32 v[66:67], v[74:75], v[66:67]
	v_lshlrev_b32_e32 v70, 16, v72
	v_and_b32_e32 v71, 0xffff0000, v72
	v_lshlrev_b32_e32 v72, 16, v73
	v_and_b32_e32 v73, 0xffff0000, v73
	v_pk_fma_f32 v[78:79], v[30:31], v[86:87], v[78:79]
	v_pk_fma_f32 v[80:81], v[32:33], v[88:89], v[80:81]
	v_pk_mul_f32 v[68:69], v[76:77], v[68:69]
	v_cvt_pk_bf16_f32 v66, v66, v67
	v_cmp_gt_i32_e32 vcc, s30, v132
	v_pk_mul_f32 v[72:73], v[80:81], v[72:73]
	v_pk_mul_f32 v[70:71], v[78:79], v[70:71]
	v_cvt_pk_bf16_f32 v67, v68, v69
	s_nop 0
	v_cvt_pk_bf16_f32 v68, v70, v71
	v_cvt_pk_bf16_f32 v69, v72, v73
	global_store_dwordx4 v[148:149], v[66:69], off nt
	s_nop 1
	v_cndmask_b32_e32 v66, 31, v115, vcc
	v_and_b32_e32 v66, v66, v146
	v_cmp_ne_u32_e64 s[0:1], 0, v66
	s_nor_b64 s[12:13], vcc, s[0:1]
	s_nop 0
	v_cndmask_b32_e64 v66, 0, v6, s[0:1]
	v_cndmask_b32_e64 v67, 0, v7, s[0:1]
	v_cndmask_b32_e64 v68, 0, v8, s[0:1]
	v_cndmask_b32_e64 v69, 0, v9, s[0:1]
	v_cndmask_b32_e64 v70, 0, v2, s[0:1]
	v_cndmask_b32_e64 v71, 0, v3, s[0:1]
	v_cndmask_b32_e64 v72, 0, v4, s[0:1]
	v_cndmask_b32_e64 v73, 0, v5, s[0:1]
	v_cndmask_b32_e64 v5, 0, v89, s[0:1]
	v_cndmask_b32_e64 v4, 0, v88, s[0:1]
	v_cndmask_b32_e64 v3, 0, v87, s[0:1]
	v_cndmask_b32_e64 v2, 0, v86, s[0:1]
	v_cndmask_b32_e64 v9, 0, v85, s[0:1]
	v_cndmask_b32_e64 v8, 0, v84, s[0:1]
	v_cndmask_b32_e64 v7, 0, v83, s[0:1]
	v_cndmask_b32_e64 v6, 0, v82, s[0:1]
	s_and_saveexec_b64 s[0:1], s[12:13]
	s_cbranch_execz .LBB0_847
	v_add_u32_e32 v2, 0xffffc005, v132
	v_lshrrev_b32_e32 v2, 4, v2
	v_and_b32_e32 v122, 0xffffffe, v2
	v_lshlrev_b64 v[2:3], 12, v[122:123]
	v_lshl_add_u64 v[2:3], v[128:129], 0, v[2:3]
	global_load_dwordx4 v[66:69], v[2:3], off
	global_load_dwordx4 v[70:73], v[2:3], off offset:16
	v_lshl_add_u64 v[4:5], v[2:3], 0, s[24:25]
	v_add_co_u32_e32 v2, vcc, 0x1000, v2
	s_nop 1
	v_addc_co_u32_e32 v3, vcc, 0, v3, vcc
	global_load_dwordx4 v[6:9], v[2:3], off
	s_nop 0
	global_load_dwordx4 v[2:5], v[4:5], off offset:16
.LBB0_847:
	s_or_b64 exec, exec, s[0:1]
	s_waitcnt vmcnt(1)
	v_pk_mul_f32 v[82:83], v[20:21], v[8:9]
	s_waitcnt vmcnt(0)
	v_pk_mul_f32 v[84:85], v[26:27], v[2:3]
	v_pk_mul_f32 v[86:87], v[28:29], v[4:5]
	v_pk_mul_f32 v[88:89], v[18:19], v[6:7]
	v_lshlrev_b32_e32 v74, 16, v62
	v_and_b32_e32 v75, 0xffff0000, v62
	v_lshlrev_b32_e32 v76, 16, v63
	v_and_b32_e32 v77, 0xffff0000, v63
	v_lshlrev_b32_e32 v78, 16, v64
	v_and_b32_e32 v79, 0xffff0000, v64
	v_lshlrev_b32_e32 v80, 16, v65
	v_and_b32_e32 v81, 0xffff0000, v65
	v_pk_fma_f32 v[72:73], v[12:13], v[72:73], v[86:87]
	v_pk_fma_f32 v[70:71], v[10:11], v[70:71], v[84:85]
	v_pk_fma_f32 v[68:69], v[16:17], v[68:69], v[82:83]
	v_pk_fma_f32 v[66:67], v[14:15], v[66:67], v[88:89]
	v_lshlrev_b32_e32 v62, 16, v58
	v_and_b32_e32 v63, 0xffff0000, v58
	v_lshlrev_b32_e32 v58, 16, v59
	v_and_b32_e32 v59, 0xffff0000, v59
	v_lshlrev_b32_e32 v64, 16, v60
	v_and_b32_e32 v65, 0xffff0000, v60
	v_lshlrev_b32_e32 v60, 16, v61
	v_and_b32_e32 v61, 0xffff0000, v61
	v_pk_fma_f32 v[66:67], v[22:23], v[74:75], v[66:67]
	v_pk_fma_f32 v[68:69], v[24:25], v[76:77], v[68:69]
	v_pk_fma_f32 v[70:71], v[30:31], v[78:79], v[70:71]
	v_pk_fma_f32 v[72:73], v[32:33], v[80:81], v[72:73]
	v_cmp_gt_i32_e32 vcc, s31, v132
	v_pk_mul_f32 v[72:73], v[72:73], v[60:61]
	v_pk_mul_f32 v[60:61], v[70:71], v[64:65]
	v_pk_mul_f32 v[64:65], v[68:69], v[58:59]
	v_pk_mul_f32 v[58:59], v[66:67], v[62:63]
	s_nop 0
	v_cvt_pk_bf16_f32 v58, v58, v59
	v_cvt_pk_bf16_f32 v59, v64, v65
	v_cvt_pk_bf16_f32 v60, v60, v61
	v_cvt_pk_bf16_f32 v61, v72, v73
	global_store_dwordx4 v[142:143], v[58:61], off nt
	s_nop 1
	v_cndmask_b32_e32 v58, 31, v115, vcc
	v_and_b32_e32 v58, v58, v144
	v_cmp_ne_u32_e64 s[0:1], 0, v58
	s_nor_b64 s[12:13], vcc, s[0:1]
	s_nop 0
	v_cndmask_b32_e64 v58, 0, v6, s[0:1]
	v_cndmask_b32_e64 v59, 0, v7, s[0:1]
	v_cndmask_b32_e64 v60, 0, v8, s[0:1]
	v_cndmask_b32_e64 v61, 0, v9, s[0:1]
	v_cndmask_b32_e64 v62, 0, v2, s[0:1]
	v_cndmask_b32_e64 v63, 0, v3, s[0:1]
	v_cndmask_b32_e64 v64, 0, v4, s[0:1]
	v_cndmask_b32_e64 v65, 0, v5, s[0:1]
	v_cndmask_b32_e64 v5, 0, v81, s[0:1]
	v_cndmask_b32_e64 v4, 0, v80, s[0:1]
	v_cndmask_b32_e64 v3, 0, v79, s[0:1]
	v_cndmask_b32_e64 v2, 0, v78, s[0:1]
	v_cndmask_b32_e64 v9, 0, v77, s[0:1]
	v_cndmask_b32_e64 v8, 0, v76, s[0:1]
	v_cndmask_b32_e64 v7, 0, v75, s[0:1]
	v_cndmask_b32_e64 v6, 0, v74, s[0:1]
	s_and_saveexec_b64 s[0:1], s[12:13]
	s_cbranch_execz .LBB0_849
	v_add_u32_e32 v2, 0xffffc006, v132
	v_lshrrev_b32_e32 v2, 4, v2
	v_and_b32_e32 v122, 0xffffffe, v2
	v_lshlrev_b64 v[2:3], 12, v[122:123]
	v_lshl_add_u64 v[2:3], v[128:129], 0, v[2:3]
	global_load_dwordx4 v[58:61], v[2:3], off
	global_load_dwordx4 v[62:65], v[2:3], off offset:16
	v_lshl_add_u64 v[4:5], v[2:3], 0, s[24:25]
	v_add_co_u32_e32 v2, vcc, 0x1000, v2
	s_nop 1
	v_addc_co_u32_e32 v3, vcc, 0, v3, vcc
	global_load_dwordx4 v[6:9], v[2:3], off
	s_nop 0
	global_load_dwordx4 v[2:5], v[4:5], off offset:16
.LBB0_849:
	s_or_b64 exec, exec, s[0:1]
	s_waitcnt vmcnt(1)
	v_pk_mul_f32 v[80:81], v[18:19], v[6:7]
	v_lshlrev_b32_e32 v66, 16, v50
	v_and_b32_e32 v67, 0xffff0000, v50
	v_pk_mul_f32 v[74:75], v[20:21], v[8:9]
	v_pk_fma_f32 v[58:59], v[14:15], v[58:59], v[80:81]
	v_lshlrev_b32_e32 v68, 16, v51
	v_and_b32_e32 v69, 0xffff0000, v51
	v_lshlrev_b32_e32 v50, 16, v54
	v_and_b32_e32 v51, 0xffff0000, v54
	s_waitcnt vmcnt(0)
	v_pk_mul_f32 v[76:77], v[26:27], v[2:3]
	v_pk_mul_f32 v[78:79], v[28:29], v[4:5]
	v_pk_fma_f32 v[60:61], v[16:17], v[60:61], v[74:75]
	v_pk_fma_f32 v[58:59], v[22:23], v[66:67], v[58:59]
	v_lshlrev_b32_e32 v70, 16, v52
	v_and_b32_e32 v71, 0xffff0000, v52
	v_lshlrev_b32_e32 v72, 16, v53
	v_and_b32_e32 v73, 0xffff0000, v53
	v_lshlrev_b32_e32 v52, 16, v55
	v_and_b32_e32 v53, 0xffff0000, v55
	v_pk_fma_f32 v[64:65], v[12:13], v[64:65], v[78:79]
	v_pk_fma_f32 v[62:63], v[10:11], v[62:63], v[76:77]
	v_pk_fma_f32 v[60:61], v[24:25], v[68:69], v[60:61]
	v_pk_mul_f32 v[50:51], v[58:59], v[50:51]
	v_lshlrev_b32_e32 v54, 16, v56
	v_and_b32_e32 v55, 0xffff0000, v56
	v_lshlrev_b32_e32 v56, 16, v57
	v_and_b32_e32 v57, 0xffff0000, v57
	v_pk_fma_f32 v[62:63], v[30:31], v[70:71], v[62:63]
	v_pk_fma_f32 v[64:65], v[32:33], v[72:73], v[64:65]
	v_pk_mul_f32 v[52:53], v[60:61], v[52:53]
	v_cvt_pk_bf16_f32 v50, v50, v51
	v_cmp_gt_i32_e32 vcc, s34, v132
	v_pk_mul_f32 v[56:57], v[64:65], v[56:57]
	v_pk_mul_f32 v[54:55], v[62:63], v[54:55]
	v_cvt_pk_bf16_f32 v51, v52, v53
	s_nop 0
	v_cvt_pk_bf16_f32 v52, v54, v55
	v_cvt_pk_bf16_f32 v53, v56, v57
	global_store_dwordx4 v[140:141], v[50:53], off nt
	s_nop 1
	v_cndmask_b32_e32 v50, 31, v115, vcc
	v_and_b32_e32 v50, v50, v138
	v_cmp_ne_u32_e64 s[0:1], 0, v50
	s_nor_b64 s[12:13], vcc, s[0:1]
	s_nop 0
	v_cndmask_b32_e64 v50, 0, v6, s[0:1]
	v_cndmask_b32_e64 v51, 0, v7, s[0:1]
	v_cndmask_b32_e64 v52, 0, v8, s[0:1]
	v_cndmask_b32_e64 v53, 0, v9, s[0:1]
	v_cndmask_b32_e64 v54, 0, v2, s[0:1]
	v_cndmask_b32_e64 v55, 0, v3, s[0:1]
	v_cndmask_b32_e64 v56, 0, v4, s[0:1]
	v_cndmask_b32_e64 v57, 0, v5, s[0:1]
	v_cndmask_b32_e64 v5, 0, v73, s[0:1]
	v_cndmask_b32_e64 v4, 0, v72, s[0:1]
	v_cndmask_b32_e64 v3, 0, v71, s[0:1]
	v_cndmask_b32_e64 v2, 0, v70, s[0:1]
	v_cndmask_b32_e64 v9, 0, v69, s[0:1]
	v_cndmask_b32_e64 v8, 0, v68, s[0:1]
	v_cndmask_b32_e64 v7, 0, v67, s[0:1]
	v_cndmask_b32_e64 v6, 0, v66, s[0:1]
	s_and_saveexec_b64 s[0:1], s[12:13]
	s_cbranch_execz .LBB0_851
	v_add_u32_e32 v2, 0xffffc007, v132
	v_lshrrev_b32_e32 v2, 4, v2
	v_and_b32_e32 v122, 0xffffffe, v2
	v_lshlrev_b64 v[2:3], 12, v[122:123]
	v_lshl_add_u64 v[2:3], v[128:129], 0, v[2:3]
	global_load_dwordx4 v[50:53], v[2:3], off
	global_load_dwordx4 v[54:57], v[2:3], off offset:16
	v_lshl_add_u64 v[4:5], v[2:3], 0, s[24:25]
	v_add_co_u32_e32 v2, vcc, 0x1000, v2
	s_nop 1
	v_addc_co_u32_e32 v3, vcc, 0, v3, vcc
	global_load_dwordx4 v[6:9], v[2:3], off
	s_nop 0
	global_load_dwordx4 v[2:5], v[4:5], off offset:16
.LBB0_851:
	s_or_b64 exec, exec, s[0:1]
	s_waitcnt vmcnt(1)
	v_pk_mul_f32 v[66:67], v[20:21], v[8:9]
	s_waitcnt vmcnt(0)
	v_pk_mul_f32 v[68:69], v[26:27], v[2:3]
	v_pk_mul_f32 v[70:71], v[28:29], v[4:5]
	v_pk_mul_f32 v[72:73], v[18:19], v[6:7]
	v_lshlrev_b32_e32 v58, 16, v46
	v_and_b32_e32 v59, 0xffff0000, v46
	v_lshlrev_b32_e32 v60, 16, v47
	v_and_b32_e32 v61, 0xffff0000, v47
	v_lshlrev_b32_e32 v62, 16, v48
	v_and_b32_e32 v63, 0xffff0000, v48
	v_lshlrev_b32_e32 v64, 16, v49
	v_and_b32_e32 v65, 0xffff0000, v49
	v_pk_fma_f32 v[56:57], v[12:13], v[56:57], v[70:71]
	v_pk_fma_f32 v[54:55], v[10:11], v[54:55], v[68:69]
	v_pk_fma_f32 v[52:53], v[16:17], v[52:53], v[66:67]
	v_pk_fma_f32 v[50:51], v[14:15], v[50:51], v[72:73]
	v_lshlrev_b32_e32 v46, 16, v42
	v_and_b32_e32 v47, 0xffff0000, v42
	v_lshlrev_b32_e32 v42, 16, v43
	v_and_b32_e32 v43, 0xffff0000, v43
	v_lshlrev_b32_e32 v48, 16, v44
	v_and_b32_e32 v49, 0xffff0000, v44
	v_lshlrev_b32_e32 v44, 16, v45
	v_and_b32_e32 v45, 0xffff0000, v45
	v_pk_fma_f32 v[50:51], v[22:23], v[58:59], v[50:51]
	v_pk_fma_f32 v[52:53], v[24:25], v[60:61], v[52:53]
	v_pk_fma_f32 v[54:55], v[30:31], v[62:63], v[54:55]
	v_pk_fma_f32 v[56:57], v[32:33], v[64:65], v[56:57]
	v_cmp_gt_i32_e32 vcc, s35, v132
	v_pk_mul_f32 v[56:57], v[56:57], v[44:45]
	v_pk_mul_f32 v[44:45], v[54:55], v[48:49]
	v_pk_mul_f32 v[48:49], v[52:53], v[42:43]
	v_pk_mul_f32 v[42:43], v[50:51], v[46:47]
	s_nop 0
	v_cvt_pk_bf16_f32 v42, v42, v43
	v_cvt_pk_bf16_f32 v43, v48, v49
	v_cvt_pk_bf16_f32 v44, v44, v45
	v_cvt_pk_bf16_f32 v45, v56, v57
	global_store_dwordx4 v[134:135], v[42:45], off nt
	s_nop 1
	v_cndmask_b32_e32 v42, 31, v115, vcc
	v_and_b32_e32 v42, v42, v136
	v_cmp_ne_u32_e64 s[0:1], 0, v42
	s_nor_b64 s[12:13], vcc, s[0:1]
	s_nop 0
	v_cndmask_b32_e64 v42, 0, v6, s[0:1]
	v_cndmask_b32_e64 v43, 0, v7, s[0:1]
	v_cndmask_b32_e64 v44, 0, v8, s[0:1]
	v_cndmask_b32_e64 v45, 0, v9, s[0:1]
	v_cndmask_b32_e64 v46, 0, v2, s[0:1]
	v_cndmask_b32_e64 v47, 0, v3, s[0:1]
	v_cndmask_b32_e64 v48, 0, v4, s[0:1]
	v_cndmask_b32_e64 v49, 0, v5, s[0:1]
	v_cndmask_b32_e64 v9, 0, v65, s[0:1]
	v_cndmask_b32_e64 v8, 0, v64, s[0:1]
	v_cndmask_b32_e64 v7, 0, v63, s[0:1]
	v_cndmask_b32_e64 v6, 0, v62, s[0:1]
	v_cndmask_b32_e64 v5, 0, v61, s[0:1]
	v_cndmask_b32_e64 v4, 0, v60, s[0:1]
	v_cndmask_b32_e64 v3, 0, v59, s[0:1]
	v_cndmask_b32_e64 v2, 0, v58, s[0:1]
	s_and_saveexec_b64 s[0:1], s[12:13]
	s_cbranch_execz .LBB0_834
	v_add_u32_e32 v2, 0xffffc008, v132
	v_lshrrev_b32_e32 v2, 4, v2
	v_and_b32_e32 v122, 0xffffffe, v2
	v_lshlrev_b64 v[2:3], 12, v[122:123]
	v_lshl_add_u64 v[2:3], v[128:129], 0, v[2:3]
	global_load_dwordx4 v[42:45], v[2:3], off
	global_load_dwordx4 v[46:49], v[2:3], off offset:16
	v_lshl_add_u64 v[6:7], v[2:3], 0, s[24:25]
	v_add_co_u32_e32 v2, vcc, 0x1000, v2
	s_nop 1
	v_addc_co_u32_e32 v3, vcc, 0, v3, vcc
	global_load_dwordx4 v[2:5], v[2:3], off
	s_nop 0
	global_load_dwordx4 v[6:9], v[6:7], off offset:16
	s_branch .LBB0_834

.LBB0_856:
	s_or_b64 exec, exec, s[0:1]
	s_waitcnt vmcnt(1)
	v_pk_mul_f32 v[50:51], v[20:21], v[4:5]
	s_waitcnt vmcnt(0)
	v_pk_mul_f32 v[52:53], v[26:27], v[6:7]
	v_pk_mul_f32 v[54:55], v[28:29], v[8:9]
	v_pk_mul_f32 v[56:57], v[18:19], v[2:3]
	v_lshlrev_b32_e32 v150, 16, v38
	v_and_b32_e32 v151, 0xffff0000, v38
	v_lshlrev_b32_e32 v152, 16, v39
	v_and_b32_e32 v153, 0xffff0000, v39
	v_lshlrev_b32_e32 v154, 16, v40
	v_and_b32_e32 v155, 0xffff0000, v40
	v_lshlrev_b32_e32 v156, 16, v41
	v_and_b32_e32 v157, 0xffff0000, v41
	v_pk_fma_f32 v[48:49], v[12:13], v[48:49], v[54:55]
	v_pk_fma_f32 v[46:47], v[10:11], v[46:47], v[52:53]
	v_pk_fma_f32 v[44:45], v[16:17], v[44:45], v[50:51]
	v_pk_fma_f32 v[42:43], v[14:15], v[42:43], v[56:57]
	v_lshlrev_b32_e32 v38, 16, v34
	v_and_b32_e32 v39, 0xffff0000, v34
	v_lshlrev_b32_e32 v34, 16, v35
	v_and_b32_e32 v35, 0xffff0000, v35
	v_lshlrev_b32_e32 v40, 16, v36
	v_and_b32_e32 v41, 0xffff0000, v36
	v_lshlrev_b32_e32 v36, 16, v37
	v_and_b32_e32 v37, 0xffff0000, v37
	v_pk_fma_f32 v[42:43], v[22:23], v[150:151], v[42:43]
	v_pk_fma_f32 v[44:45], v[24:25], v[152:153], v[44:45]
	v_pk_fma_f32 v[46:47], v[30:31], v[154:155], v[46:47]
	v_pk_fma_f32 v[48:49], v[32:33], v[156:157], v[48:49]
	s_nop 0
	v_pk_mul_f32 v[48:49], v[48:49], v[36:37]
	v_pk_mul_f32 v[36:37], v[46:47], v[40:41]
	v_pk_mul_f32 v[40:41], v[44:45], v[34:35]
	v_pk_mul_f32 v[34:35], v[42:43], v[38:39]
	s_nop 0
	v_cvt_pk_bf16_f32 v34, v34, v35
	v_cvt_pk_bf16_f32 v35, v40, v41
	v_cvt_pk_bf16_f32 v36, v36, v37
	v_cvt_pk_bf16_f32 v37, v48, v49
	global_store_dwordx4 v[82:83], v[34:37], off nt
	s_nop 1
	v_add_u32_e32 v35, 8, v114
	v_add_u32_e32 v34, 4, v114
	v_cmp_gt_i32_e32 vcc, v35, v116
	s_or_b64 s[10:11], vcc, s[10:11]
	v_mov_b32_e32 v114, v34
	s_andn2_b64 exec, exec, s[10:11]
	s_cbranch_execz .LBB0_865
.LBB0_857:
	v_mov_b32_e32 v84, v114
	s_nop 0
	v_ashrrev_i32_e32 v85, 31, v84
	v_add_u32_e32 v94, 1, v84
	v_lshlrev_b64 v[34:35], 11, v[84:85]
	v_ashrrev_i32_e32 v95, 31, v94
	v_add_u32_e32 v92, 2, v84
	v_lshl_add_u64 v[36:37], v[76:77], 0, v[34:35]
	v_lshl_add_u64 v[96:97], v[78:79], 0, v[34:35]
	v_lshlrev_b64 v[34:35], 11, v[94:95]
	v_ashrrev_i32_e32 v93, 31, v92
	v_add_u32_e32 v86, 3, v84
	v_lshl_add_u64 v[38:39], v[76:77], 0, v[34:35]
	v_lshl_add_u64 v[90:91], v[78:79], 0, v[34:35]
	v_lshlrev_b64 v[34:35], 11, v[92:93]
	v_ashrrev_i32_e32 v87, 31, v86
	global_load_dwordx4 v[66:69], v[36:37], off nt
	global_load_dwordx4 v[54:57], v[38:39], off nt
	v_lshl_add_u64 v[36:37], v[76:77], 0, v[34:35]
	v_lshl_add_u64 v[88:89], v[78:79], 0, v[34:35]
	v_lshlrev_b64 v[34:35], 11, v[86:87]
	v_lshl_add_u64 v[38:39], v[76:77], 0, v[34:35]
	global_load_dwordx4 v[58:61], v[96:97], off nt
	global_load_dwordx4 v[50:53], v[90:91], off nt
	global_load_dwordx4 v[46:49], v[36:37], off nt
	s_nop 0
	global_load_dwordx4 v[38:41], v[38:39], off nt
	v_lshl_add_u64 v[82:83], v[78:79], 0, v[34:35]
	global_load_dwordx4 v[42:45], v[88:89], off nt
	global_load_dwordx4 v[34:37], v[82:83], off nt
	v_cmp_gt_i32_e32 vcc, s3, v84
	s_nop 1
	v_cndmask_b32_e32 v62, 31, v98, vcc
	v_and_b32_e32 v62, v62, v84
	v_cmp_ne_u32_e64 s[0:1], 0, v62
	s_nor_b64 s[12:13], vcc, s[0:1]
	s_nop 0
	v_cndmask_b32_e64 v62, 0, v2, s[0:1]
	v_cndmask_b32_e64 v63, 0, v3, s[0:1]
	v_cndmask_b32_e64 v64, 0, v4, s[0:1]
	v_cndmask_b32_e64 v65, 0, v5, s[0:1]
	v_cndmask_b32_e64 v70, 0, v6, s[0:1]
	v_cndmask_b32_e64 v71, 0, v7, s[0:1]
	v_cndmask_b32_e64 v72, 0, v8, s[0:1]
	v_cndmask_b32_e64 v73, 0, v9, s[0:1]
	v_cndmask_b32_e64 v5, 0, v157, s[0:1]
	v_cndmask_b32_e64 v4, 0, v156, s[0:1]
	v_cndmask_b32_e64 v3, 0, v155, s[0:1]
	v_cndmask_b32_e64 v2, 0, v154, s[0:1]
	v_cndmask_b32_e64 v9, 0, v153, s[0:1]
	v_cndmask_b32_e64 v8, 0, v152, s[0:1]
	v_cndmask_b32_e64 v7, 0, v151, s[0:1]
	v_cndmask_b32_e64 v6, 0, v150, s[0:1]
	s_and_saveexec_b64 s[0:1], s[12:13]
	s_cbranch_execz .LBB0_859
	v_add_u32_e32 v2, 0xffffc000, v84
	v_lshrrev_b32_e32 v2, 4, v2
	v_and_b32_e32 v74, 0xffffffe, v2
	v_lshlrev_b64 v[2:3], 12, v[74:75]
	v_lshl_add_u64 v[2:3], v[80:81], 0, v[2:3]
	global_load_dwordx4 v[62:65], v[2:3], off
	global_load_dwordx4 v[70:73], v[2:3], off offset:16
	v_lshl_add_u64 v[4:5], v[2:3], 0, s[24:25]
	v_add_co_u32_e32 v2, vcc, 0x1000, v2
	s_nop 1
	v_addc_co_u32_e32 v3, vcc, 0, v3, vcc
	global_load_dwordx4 v[6:9], v[2:3], off
	s_nop 0
	global_load_dwordx4 v[2:5], v[4:5], off offset:16
.LBB0_859:
	s_or_b64 exec, exec, s[0:1]
	s_waitcnt vmcnt(1)
	v_pk_mul_f32 v[108:109], v[20:21], v[8:9]
	v_pk_mul_f32 v[122:123], v[18:19], v[6:7]
	v_lshlrev_b32_e32 v100, 16, v66
	v_and_b32_e32 v101, 0xffff0000, v66
	v_lshlrev_b32_e32 v66, 16, v67
	v_and_b32_e32 v67, 0xffff0000, v67
	s_waitcnt vmcnt(0)
	v_pk_mul_f32 v[110:111], v[26:27], v[2:3]
	v_pk_mul_f32 v[112:113], v[28:29], v[4:5]
	v_pk_fma_f32 v[64:65], v[16:17], v[64:65], v[108:109]
	v_pk_fma_f32 v[62:63], v[14:15], v[62:63], v[122:123]
	v_lshlrev_b32_e32 v102, 16, v68
	v_and_b32_e32 v103, 0xffff0000, v68
	v_lshlrev_b32_e32 v68, 16, v69
	v_and_b32_e32 v69, 0xffff0000, v69
	v_lshlrev_b32_e32 v104, 16, v58
	v_and_b32_e32 v105, 0xffff0000, v58
	v_lshlrev_b32_e32 v58, 16, v59
	v_and_b32_e32 v59, 0xffff0000, v59
	v_pk_fma_f32 v[72:73], v[12:13], v[72:73], v[112:113]
	v_pk_fma_f32 v[70:71], v[10:11], v[70:71], v[110:111]
	v_pk_fma_f32 v[62:63], v[22:23], v[100:101], v[62:63]
	v_pk_fma_f32 v[64:65], v[24:25], v[66:67], v[64:65]
	v_lshlrev_b32_e32 v106, 16, v60
	v_and_b32_e32 v107, 0xffff0000, v60
	v_lshlrev_b32_e32 v60, 16, v61
	v_and_b32_e32 v61, 0xffff0000, v61
	v_pk_fma_f32 v[70:71], v[30:31], v[102:103], v[70:71]
	v_pk_fma_f32 v[72:73], v[32:33], v[68:69], v[72:73]
	v_pk_mul_f32 v[64:65], v[64:65], v[58:59]
	v_pk_mul_f32 v[58:59], v[62:63], v[104:105]
	v_pk_mul_f32 v[72:73], v[72:73], v[60:61]
	v_pk_mul_f32 v[60:61], v[70:71], v[106:107]
	v_cvt_pk_bf16_f32 v58, v58, v59
	v_cmp_gt_i32_e32 vcc, s26, v84
	v_cvt_pk_bf16_f32 v59, v64, v65
	v_cvt_pk_bf16_f32 v60, v60, v61
	v_cvt_pk_bf16_f32 v61, v72, v73
	global_store_dwordx4 v[96:97], v[58:61], off nt
	s_nop 1
	v_cndmask_b32_e32 v58, 31, v98, vcc
	v_and_b32_e32 v58, v58, v94
	v_cmp_ne_u32_e64 s[0:1], 0, v58
	s_nor_b64 s[12:13], vcc, s[0:1]
	s_nop 0
	v_cndmask_b32_e64 v58, 0, v6, s[0:1]
	v_cndmask_b32_e64 v59, 0, v7, s[0:1]
	v_cndmask_b32_e64 v60, 0, v8, s[0:1]
	v_cndmask_b32_e64 v61, 0, v9, s[0:1]
	v_cndmask_b32_e64 v62, 0, v2, s[0:1]
	v_cndmask_b32_e64 v63, 0, v3, s[0:1]
	v_cndmask_b32_e64 v64, 0, v4, s[0:1]
	v_cndmask_b32_e64 v65, 0, v5, s[0:1]
	v_cndmask_b32_e64 v5, 0, v69, s[0:1]
	v_cndmask_b32_e64 v4, 0, v68, s[0:1]
	v_cndmask_b32_e64 v3, 0, v103, s[0:1]
	v_cndmask_b32_e64 v2, 0, v102, s[0:1]
	v_cndmask_b32_e64 v9, 0, v67, s[0:1]
	v_cndmask_b32_e64 v8, 0, v66, s[0:1]
	v_cndmask_b32_e64 v7, 0, v101, s[0:1]
	v_cndmask_b32_e64 v6, 0, v100, s[0:1]
	s_and_saveexec_b64 s[0:1], s[12:13]
	s_cbranch_execz .LBB0_861
	v_add_u32_e32 v2, 0xffffc001, v84
	v_lshrrev_b32_e32 v2, 4, v2
	v_and_b32_e32 v74, 0xffffffe, v2
	v_lshlrev_b64 v[2:3], 12, v[74:75]
	v_lshl_add_u64 v[2:3], v[80:81], 0, v[2:3]
	global_load_dwordx4 v[58:61], v[2:3], off
	global_load_dwordx4 v[62:65], v[2:3], off offset:16
	v_lshl_add_u64 v[4:5], v[2:3], 0, s[24:25]
	v_add_co_u32_e32 v2, vcc, 0x1000, v2
	s_nop 1
	v_addc_co_u32_e32 v3, vcc, 0, v3, vcc
	global_load_dwordx4 v[6:9], v[2:3], off
	s_nop 0
	global_load_dwordx4 v[2:5], v[4:5], off offset:16
.LBB0_861:
	s_or_b64 exec, exec, s[0:1]
	s_waitcnt vmcnt(1)
	v_pk_mul_f32 v[94:95], v[20:21], v[8:9]
	s_waitcnt vmcnt(0)
	v_pk_mul_f32 v[96:97], v[26:27], v[2:3]
	v_pk_mul_f32 v[100:101], v[28:29], v[4:5]
	v_pk_mul_f32 v[102:103], v[18:19], v[6:7]
	v_lshlrev_b32_e32 v66, 16, v54
	v_and_b32_e32 v67, 0xffff0000, v54
	v_lshlrev_b32_e32 v68, 16, v55
	v_and_b32_e32 v69, 0xffff0000, v55
	v_lshlrev_b32_e32 v70, 16, v56
	v_and_b32_e32 v71, 0xffff0000, v56
	v_lshlrev_b32_e32 v72, 16, v57
	v_and_b32_e32 v73, 0xffff0000, v57
	v_pk_fma_f32 v[64:65], v[12:13], v[64:65], v[100:101]
	v_pk_fma_f32 v[62:63], v[10:11], v[62:63], v[96:97]
	v_pk_fma_f32 v[60:61], v[16:17], v[60:61], v[94:95]
	v_pk_fma_f32 v[58:59], v[14:15], v[58:59], v[102:103]
	v_lshlrev_b32_e32 v54, 16, v50
	v_and_b32_e32 v55, 0xffff0000, v50
	v_lshlrev_b32_e32 v50, 16, v51
	v_and_b32_e32 v51, 0xffff0000, v51
	v_lshlrev_b32_e32 v56, 16, v52
	v_and_b32_e32 v57, 0xffff0000, v52
	v_lshlrev_b32_e32 v52, 16, v53
	v_and_b32_e32 v53, 0xffff0000, v53
	v_pk_fma_f32 v[58:59], v[22:23], v[66:67], v[58:59]
	v_pk_fma_f32 v[60:61], v[24:25], v[68:69], v[60:61]
	v_pk_fma_f32 v[62:63], v[30:31], v[70:71], v[62:63]
	v_pk_fma_f32 v[64:65], v[32:33], v[72:73], v[64:65]
	v_cmp_gt_i32_e32 vcc, s27, v84
	v_pk_mul_f32 v[64:65], v[64:65], v[52:53]
	v_pk_mul_f32 v[52:53], v[62:63], v[56:57]
	v_pk_mul_f32 v[56:57], v[60:61], v[50:51]
	v_pk_mul_f32 v[50:51], v[58:59], v[54:55]
	s_nop 0
	v_cvt_pk_bf16_f32 v50, v50, v51
	v_cvt_pk_bf16_f32 v51, v56, v57
	v_cvt_pk_bf16_f32 v52, v52, v53
	v_cvt_pk_bf16_f32 v53, v64, v65
	global_store_dwordx4 v[90:91], v[50:53], off nt
	s_nop 1
	v_cndmask_b32_e32 v50, 31, v98, vcc
	v_and_b32_e32 v50, v50, v92
	v_cmp_ne_u32_e64 s[0:1], 0, v50
	s_nor_b64 s[12:13], vcc, s[0:1]
	s_nop 0
	v_cndmask_b32_e64 v50, 0, v6, s[0:1]
	v_cndmask_b32_e64 v51, 0, v7, s[0:1]
	v_cndmask_b32_e64 v52, 0, v8, s[0:1]
	v_cndmask_b32_e64 v53, 0, v9, s[0:1]
	v_cndmask_b32_e64 v54, 0, v2, s[0:1]
	v_cndmask_b32_e64 v55, 0, v3, s[0:1]
	v_cndmask_b32_e64 v56, 0, v4, s[0:1]
	v_cndmask_b32_e64 v57, 0, v5, s[0:1]
	v_cndmask_b32_e64 v5, 0, v73, s[0:1]
	v_cndmask_b32_e64 v4, 0, v72, s[0:1]
	v_cndmask_b32_e64 v3, 0, v71, s[0:1]
	v_cndmask_b32_e64 v2, 0, v70, s[0:1]
	v_cndmask_b32_e64 v9, 0, v69, s[0:1]
	v_cndmask_b32_e64 v8, 0, v68, s[0:1]
	v_cndmask_b32_e64 v7, 0, v67, s[0:1]
	v_cndmask_b32_e64 v6, 0, v66, s[0:1]
	s_and_saveexec_b64 s[0:1], s[12:13]
	s_cbranch_execz .LBB0_863
	v_add_u32_e32 v2, 0xffffc002, v84
	v_lshrrev_b32_e32 v2, 4, v2
	v_and_b32_e32 v74, 0xffffffe, v2
	v_lshlrev_b64 v[2:3], 12, v[74:75]
	v_lshl_add_u64 v[2:3], v[80:81], 0, v[2:3]
	global_load_dwordx4 v[50:53], v[2:3], off
	global_load_dwordx4 v[54:57], v[2:3], off offset:16
	v_lshl_add_u64 v[4:5], v[2:3], 0, s[24:25]
	v_add_co_u32_e32 v2, vcc, 0x1000, v2
	s_nop 1
	v_addc_co_u32_e32 v3, vcc, 0, v3, vcc
	global_load_dwordx4 v[6:9], v[2:3], off
	s_nop 0
	global_load_dwordx4 v[2:5], v[4:5], off offset:16
.LBB0_863:
	s_or_b64 exec, exec, s[0:1]
	s_waitcnt vmcnt(1)
	v_pk_mul_f32 v[66:67], v[20:21], v[8:9]
	s_waitcnt vmcnt(0)
	v_pk_mul_f32 v[68:69], v[26:27], v[2:3]
	v_pk_mul_f32 v[70:71], v[28:29], v[4:5]
	v_pk_mul_f32 v[72:73], v[18:19], v[6:7]
	v_lshlrev_b32_e32 v58, 16, v46
	v_and_b32_e32 v59, 0xffff0000, v46
	v_lshlrev_b32_e32 v60, 16, v47
	v_and_b32_e32 v61, 0xffff0000, v47
	v_lshlrev_b32_e32 v62, 16, v48
	v_and_b32_e32 v63, 0xffff0000, v48
	v_lshlrev_b32_e32 v64, 16, v49
	v_and_b32_e32 v65, 0xffff0000, v49
	v_pk_fma_f32 v[56:57], v[12:13], v[56:57], v[70:71]
	v_pk_fma_f32 v[54:55], v[10:11], v[54:55], v[68:69]
	v_pk_fma_f32 v[52:53], v[16:17], v[52:53], v[66:67]
	v_pk_fma_f32 v[50:51], v[14:15], v[50:51], v[72:73]
	v_lshlrev_b32_e32 v46, 16, v42
	v_and_b32_e32 v47, 0xffff0000, v42
	v_lshlrev_b32_e32 v42, 16, v43
	v_and_b32_e32 v43, 0xffff0000, v43
	v_lshlrev_b32_e32 v48, 16, v44
	v_and_b32_e32 v49, 0xffff0000, v44
	v_lshlrev_b32_e32 v44, 16, v45
	v_and_b32_e32 v45, 0xffff0000, v45
	v_pk_fma_f32 v[50:51], v[22:23], v[58:59], v[50:51]
	v_pk_fma_f32 v[52:53], v[24:25], v[60:61], v[52:53]
	v_pk_fma_f32 v[54:55], v[30:31], v[62:63], v[54:55]
	v_pk_fma_f32 v[56:57], v[32:33], v[64:65], v[56:57]
	v_cmp_gt_i32_e32 vcc, s28, v84
	v_pk_mul_f32 v[56:57], v[56:57], v[44:45]
	v_pk_mul_f32 v[44:45], v[54:55], v[48:49]
	v_pk_mul_f32 v[48:49], v[52:53], v[42:43]
	v_pk_mul_f32 v[42:43], v[50:51], v[46:47]
	s_nop 0
	v_cvt_pk_bf16_f32 v42, v42, v43
	v_cvt_pk_bf16_f32 v43, v48, v49
	v_cvt_pk_bf16_f32 v44, v44, v45
	v_cvt_pk_bf16_f32 v45, v56, v57
	global_store_dwordx4 v[88:89], v[42:45], off nt
	s_nop 1
	v_cndmask_b32_e32 v42, 31, v98, vcc
	v_and_b32_e32 v42, v42, v86
	v_cmp_ne_u32_e64 s[0:1], 0, v42
	s_nor_b64 s[12:13], vcc, s[0:1]
	s_nop 0
	v_cndmask_b32_e64 v42, 0, v6, s[0:1]
	v_cndmask_b32_e64 v43, 0, v7, s[0:1]
	v_cndmask_b32_e64 v44, 0, v8, s[0:1]
	v_cndmask_b32_e64 v45, 0, v9, s[0:1]
	v_cndmask_b32_e64 v46, 0, v2, s[0:1]
	v_cndmask_b32_e64 v47, 0, v3, s[0:1]
	v_cndmask_b32_e64 v48, 0, v4, s[0:1]
	v_cndmask_b32_e64 v49, 0, v5, s[0:1]
	v_cndmask_b32_e64 v9, 0, v65, s[0:1]
	v_cndmask_b32_e64 v8, 0, v64, s[0:1]
	v_cndmask_b32_e64 v7, 0, v63, s[0:1]
	v_cndmask_b32_e64 v6, 0, v62, s[0:1]
	v_cndmask_b32_e64 v5, 0, v61, s[0:1]
	v_cndmask_b32_e64 v4, 0, v60, s[0:1]
	v_cndmask_b32_e64 v3, 0, v59, s[0:1]
	v_cndmask_b32_e64 v2, 0, v58, s[0:1]
	s_and_saveexec_b64 s[0:1], s[12:13]
	s_cbranch_execz .LBB0_856
	v_add_u32_e32 v2, 0xffffc003, v84
	v_lshrrev_b32_e32 v2, 4, v2
	v_and_b32_e32 v74, 0xffffffe, v2
	v_lshlrev_b64 v[2:3], 12, v[74:75]
	v_lshl_add_u64 v[2:3], v[80:81], 0, v[2:3]
	global_load_dwordx4 v[42:45], v[2:3], off
	global_load_dwordx4 v[46:49], v[2:3], off offset:16
	v_lshl_add_u64 v[6:7], v[2:3], 0, s[24:25]
	v_add_co_u32_e32 v2, vcc, 0x1000, v2
	s_nop 1
	v_addc_co_u32_e32 v3, vcc, 0, v3, vcc
	global_load_dwordx4 v[2:5], v[2:3], off
	s_nop 0
	global_load_dwordx4 v[6:9], v[6:7], off offset:16
	s_branch .LBB0_856

.LBB0_868:
	s_or_b64 exec, exec, s[0:1]
	s_waitcnt vmcnt(1)
	v_pk_mul_f32 v[58:59], v[20:21], v[4:5]
	v_pk_mul_f32 v[66:67], v[18:19], v[2:3]
	v_lshlrev_b32_e32 v150, 16, v46
	v_and_b32_e32 v151, 0xffff0000, v46
	v_lshlrev_b32_e32 v152, 16, v47
	v_and_b32_e32 v153, 0xffff0000, v47
	s_waitcnt vmcnt(0)
	v_pk_mul_f32 v[62:63], v[26:27], v[6:7]
	v_pk_mul_f32 v[64:65], v[28:29], v[8:9]
	v_pk_fma_f32 v[36:37], v[16:17], v[36:37], v[58:59]
	v_pk_fma_f32 v[34:35], v[14:15], v[34:35], v[66:67]
	v_add_u32_e32 v114, 1, v114
	v_lshlrev_b32_e32 v154, 16, v48
	v_and_b32_e32 v155, 0xffff0000, v48
	v_lshlrev_b32_e32 v156, 16, v49
	v_and_b32_e32 v157, 0xffff0000, v49
	v_lshlrev_b32_e32 v46, 16, v42
	v_and_b32_e32 v47, 0xffff0000, v42
	v_lshlrev_b32_e32 v42, 16, v43
	v_and_b32_e32 v43, 0xffff0000, v43
	v_pk_fma_f32 v[40:41], v[12:13], v[40:41], v[64:65]
	v_pk_fma_f32 v[38:39], v[10:11], v[38:39], v[62:63]
	v_pk_fma_f32 v[34:35], v[22:23], v[150:151], v[34:35]
	v_pk_fma_f32 v[36:37], v[24:25], v[152:153], v[36:37]
	v_cmp_ge_i32_e32 vcc, v114, v116
	v_lshlrev_b32_e32 v48, 16, v44
	v_and_b32_e32 v49, 0xffff0000, v44
	v_lshlrev_b32_e32 v44, 16, v45
	v_and_b32_e32 v45, 0xffff0000, v45
	v_pk_fma_f32 v[38:39], v[30:31], v[154:155], v[38:39]
	v_pk_fma_f32 v[40:41], v[32:33], v[156:157], v[40:41]
	v_pk_mul_f32 v[36:37], v[36:37], v[42:43]
	v_pk_mul_f32 v[34:35], v[34:35], v[46:47]
	s_or_b64 s[10:11], vcc, s[10:11]
	v_pk_mul_f32 v[40:41], v[40:41], v[44:45]
	v_pk_mul_f32 v[38:39], v[38:39], v[48:49]
	v_cvt_pk_bf16_f32 v34, v34, v35
	v_cvt_pk_bf16_f32 v35, v36, v37
	s_nop 0
	v_cvt_pk_bf16_f32 v36, v38, v39
	v_cvt_pk_bf16_f32 v37, v40, v41
	global_store_dwordx4 v[56:57], v[34:37], off nt
	s_andn2_b64 exec, exec, s[10:11]
	s_cbranch_execz .LBB0_871
.LBB0_869:
	v_mov_b32_e32 v58, v114
	s_nop 0
	v_ashrrev_i32_e32 v59, 31, v58
	v_lshlrev_b64 v[34:35], 11, v[58:59]
	v_lshl_add_u64 v[36:37], v[50:51], 0, v[34:35]
	v_lshl_add_u64 v[56:57], v[52:53], 0, v[34:35]
	global_load_dwordx4 v[46:49], v[36:37], off nt
	global_load_dwordx4 v[42:45], v[56:57], off nt
	v_cmp_gt_i32_e32 vcc, s2, v58
	s_nop 1
	v_cndmask_b32_e32 v34, 31, v60, vcc
	v_and_b32_e32 v34, v34, v58
	v_cmp_ne_u32_e64 s[0:1], 0, v34
	s_nor_b64 s[14:15], vcc, s[0:1]
	s_nop 0
	v_cndmask_b32_e64 v34, 0, v2, s[0:1]
	v_cndmask_b32_e64 v35, 0, v3, s[0:1]
	v_cndmask_b32_e64 v36, 0, v4, s[0:1]
	v_cndmask_b32_e64 v37, 0, v5, s[0:1]
	v_cndmask_b32_e64 v38, 0, v6, s[0:1]
	v_cndmask_b32_e64 v39, 0, v7, s[0:1]
	v_cndmask_b32_e64 v40, 0, v8, s[0:1]
	v_cndmask_b32_e64 v41, 0, v9, s[0:1]
	v_cndmask_b32_e64 v9, 0, v157, s[0:1]
	v_cndmask_b32_e64 v8, 0, v156, s[0:1]
	v_cndmask_b32_e64 v7, 0, v155, s[0:1]
	v_cndmask_b32_e64 v6, 0, v154, s[0:1]
	v_cndmask_b32_e64 v5, 0, v153, s[0:1]
	v_cndmask_b32_e64 v4, 0, v152, s[0:1]
	v_cndmask_b32_e64 v3, 0, v151, s[0:1]
	v_cndmask_b32_e64 v2, 0, v150, s[0:1]
	s_and_saveexec_b64 s[0:1], s[14:15]
	s_cbranch_execz .LBB0_868
	v_add_u32_e32 v2, 0xffffc000, v58
	v_lshrrev_b32_e32 v2, 4, v2
	v_and_b32_e32 v118, 0xffffffe, v2
	v_lshlrev_b64 v[2:3], 12, v[118:119]
	v_lshl_add_u64 v[2:3], v[54:55], 0, v[2:3]
	v_lshl_add_u64 v[6:7], v[2:3], 0, s[12:13]
	global_load_dwordx4 v[34:37], v[2:3], off
	global_load_dwordx4 v[38:41], v[2:3], off offset:16
	v_add_co_u32_e32 v2, vcc, 0x1000, v2
	s_nop 1
	v_addc_co_u32_e32 v3, vcc, 0, v3, vcc
	global_load_dwordx4 v[2:5], v[2:3], off
	s_nop 0
	global_load_dwordx4 v[6:9], v[6:7], off offset:16
	s_branch .LBB0_868
